# speedup vs baseline: 1.0035x; 1.0035x over previous
; __device__ __forceinline__ unsigned pk2(float lo, float hi) { f32x2_t v = {lo, hi}; bf16x2_t b = __builtin_convertvector(v, bf16x2_t); return __builtin_bit_cast(unsigned, b); }
; __device__ __forceinline__ float xsum32(float v) { auto rr = __builtin_amdgcn_permlane32_swap(__float_as_uint(v), __float_as_uint(v), false, false); return __uint_as_float(rr[0]) + __uint_as_float(rr[1]); }
; template <int DQK, class Pol, bool NOMAX = false> ...
;     ...
;     const float lt = xsum32(lrun), inv = 1.0f / lt;
; #pragma unroll
;     for (int g4 = 0; g4 < 4; ++g4) {
;         u32x2 w0, w1;
;         w0.x = pk2(o0[4 * g4] * inv, o0[4 * g4 + 1] * inv); w0.y = pk2(o0[4 * g4 + 2] * inv, o0[4 * g4 + 3] * inv);
;         w1.x = pk2(o1[4 * g4] * inv, o1[4 * g4 + 1] * inv); w1.y = pk2(o1[4 * g4 + 2] * inv, o1[4 * g4 + 3] * inv);
;         *(u32x2*)(Og + 8 * g4 + 4 * h) = w0; *(u32x2*)(Og + 32 + 8 * g4 + 4 * h) = w1;
;     }
.LBB0_374:
	v_add_f32_e32 v0, v101, v0
	v_div_scale_f32 v36, s[2:3], v0, v0, 1.0
	v_rcp_f32_e32 v37, v36
	v_ashrrev_i32_e32 v99, 31, v98
	v_readlane_b32 s2, v246, 1
	s_lshl_b32 s0, s63, 6
	v_fma_f32 v38, -v36, v37, 1.0
	v_fmac_f32_e32 v37, v38, v37
	v_div_scale_f32 v38, vcc, 1.0, v0, 1.0
	v_mul_f32_e32 v39, v38, v37
	v_fma_f32 v40, -v36, v39, v38
	v_fmac_f32_e32 v39, v40, v37
	v_fma_f32 v36, -v36, v39, v38
	v_lshlrev_b64 v[34:35], 11, v[98:99]
	v_readlane_b32 s3, v246, 2
	v_div_fmas_f32 v36, v36, v37, v39
	s_lshl_b32 s38, s0, 1
	v_lshl_add_u64 v[34:35], s[2:3], 0, v[34:35]
	v_div_fixup_f32 v0, v36, v0, 1.0
	v_lshl_add_u64 v[34:35], v[34:35], 0, s[38:39]
	v_mov_b32_e32 v101, v1
	v_lshl_add_u64 v[34:35], v[100:101], 1, v[34:35]
	v_lshl_add_u64 v[34:35], v[100:101], 1, v[34:35]
	v_pk_mul_f32 v[18:19], v[18:19], v[0:1] op_sel_hi:[1,0]
	v_pk_mul_f32 v[20:21], v[20:21], v[0:1] op_sel_hi:[1,0]
	v_pk_mul_f32 v[22:23], v[22:23], v[0:1] op_sel_hi:[1,0]
	v_pk_mul_f32 v[24:25], v[24:25], v[0:1] op_sel_hi:[1,0]
	v_cvt_pk_bf16_f32 v18, v18, v19
	v_cvt_pk_bf16_f32 v19, v20, v21
	v_cvt_pk_bf16_f32 v20, v22, v23
	v_cvt_pk_bf16_f32 v21, v24, v25
	s_nop 1
	v_permlane32_swap_b32_e32 v18, v20
	v_permlane32_swap_b32_e32 v19, v21
	global_store_dwordx4 v[34:35], v[18:21], off
	v_pk_mul_f32 v[2:3], v[2:3], v[0:1] op_sel_hi:[1,0]
	v_pk_mul_f32 v[4:5], v[4:5], v[0:1] op_sel_hi:[1,0]
	v_pk_mul_f32 v[6:7], v[6:7], v[0:1] op_sel_hi:[1,0]
	v_pk_mul_f32 v[8:9], v[8:9], v[0:1] op_sel_hi:[1,0]
	v_cvt_pk_bf16_f32 v2, v2, v3
	v_cvt_pk_bf16_f32 v3, v4, v5
	v_cvt_pk_bf16_f32 v4, v6, v7
	v_cvt_pk_bf16_f32 v5, v8, v9
	s_nop 1
	v_permlane32_swap_b32_e32 v2, v4
	v_permlane32_swap_b32_e32 v3, v5
	global_store_dwordx4 v[34:35], v[2:5], off offset:64
	v_pk_mul_f32 v[26:27], v[26:27], v[0:1] op_sel_hi:[1,0]
	v_pk_mul_f32 v[28:29], v[28:29], v[0:1] op_sel_hi:[1,0]
	v_pk_mul_f32 v[30:31], v[30:31], v[0:1] op_sel_hi:[1,0]
	v_pk_mul_f32 v[32:33], v[32:33], v[0:1] op_sel_hi:[1,0]
	v_cvt_pk_bf16_f32 v26, v26, v27
	v_cvt_pk_bf16_f32 v27, v28, v29
	v_cvt_pk_bf16_f32 v28, v30, v31
	v_cvt_pk_bf16_f32 v29, v32, v33
	s_nop 1
	v_permlane32_swap_b32_e32 v26, v28
	v_permlane32_swap_b32_e32 v27, v29
	global_store_dwordx4 v[34:35], v[26:29], off offset:32
	v_pk_mul_f32 v[10:11], v[10:11], v[0:1] op_sel_hi:[1,0]
	v_pk_mul_f32 v[12:13], v[12:13], v[0:1] op_sel_hi:[1,0]
	v_pk_mul_f32 v[14:15], v[14:15], v[0:1] op_sel_hi:[1,0]
	v_pk_mul_f32 v[16:17], v[16:17], v[0:1] op_sel_hi:[1,0]
	v_cvt_pk_bf16_f32 v10, v10, v11
	v_cvt_pk_bf16_f32 v11, v12, v13
	v_cvt_pk_bf16_f32 v12, v14, v15
	v_cvt_pk_bf16_f32 v13, v16, v17
	s_nop 1
	v_permlane32_swap_b32_e32 v10, v12
	v_permlane32_swap_b32_e32 v11, v13
	global_store_dwordx4 v[34:35], v[10:13], off offset:96
	s_add_i32 s62, s62, 1
	v_readlane_b32 s4, v246, 3
	v_readlane_b32 s1, v246, 7
	s_nop 3
	s_mul_i32 s0, s62, s4
	s_add_i32 s80, s0, s1
	s_add_i32 s54, s54, s55
	s_add_i32 s61, s61, s4
	s_cmpk_gt_i32 s80, 0x5ff
	v_readlane_b32 s5, v246, 4
	s_cbranch_scc1 .LBB0_421

; __device__ __forceinline__ unsigned pk2(float lo, float hi) { f32x2_t v = {lo, hi}; bf16x2_t b = __builtin_convertvector(v, bf16x2_t); return __builtin_bit_cast(unsigned, b); }
; __device__ __forceinline__ float xsum32(float v) { auto rr = __builtin_amdgcn_permlane32_swap(__float_as_uint(v), __float_as_uint(v), false, false); return __uint_as_float(rr[0]) + __uint_as_float(rr[1]); }
; template <int DQK, class Pol, bool NOMAX = false> ...
;     ...
;     const float lt = xsum32(lrun), inv = 1.0f / lt;
; #pragma unroll
;     for (int g4 = 0; g4 < 4; ++g4) {
;         u32x2 w0, w1;
;         w0.x = pk2(o0[4 * g4] * inv, o0[4 * g4 + 1] * inv); w0.y = pk2(o0[4 * g4 + 2] * inv, o0[4 * g4 + 3] * inv);
;         w1.x = pk2(o1[4 * g4] * inv, o1[4 * g4 + 1] * inv); w1.y = pk2(o1[4 * g4 + 2] * inv, o1[4 * g4 + 3] * inv);
;         *(u32x2*)(Og + 8 * g4 + 4 * h) = w0; *(u32x2*)(Og + 32 + 8 * g4 + 4 * h) = w1;
;     }
.LBB0_424:
	s_lshl_b32 s4, s14, 6
	v_add_f32_e32 v1, v95, v1
	s_lshl_b32 s44, s4, 1
	v_div_scale_f32 v36, s[4:5], v1, v1, 1.0
	v_rcp_f32_e32 v37, v36
	v_ashrrev_i32_e32 v97, 31, v96
	v_readlane_b32 s8, v246, 1
	v_lshlrev_b64 v[34:35], 11, v[96:97]
	v_fma_f32 v38, -v36, v37, 1.0
	v_fmac_f32_e32 v37, v38, v37
	v_div_scale_f32 v38, vcc, 1.0, v1, 1.0
	v_mul_f32_e32 v39, v38, v37
	v_fma_f32 v40, -v36, v39, v38
	v_fmac_f32_e32 v39, v40, v37
	v_fma_f32 v36, -v36, v39, v38
	v_readlane_b32 s9, v246, 2
	v_div_fmas_f32 v36, v36, v37, v39
	v_div_fixup_f32 v36, v36, v1, 1.0
	v_lshl_add_u64 v[34:35], s[8:9], 0, v[34:35]
	v_lshl_add_u64 v[34:35], v[34:35], 0, s[44:45]
	v_mov_b32_e32 v99, v0
	v_lshl_add_u64 v[34:35], v[98:99], 1, v[34:35]
	v_lshl_add_u64 v[34:35], v[98:99], 1, v[34:35]
	v_pk_mul_f32 v[18:19], v[18:19], v[36:37] op_sel_hi:[1,0]
	v_pk_mul_f32 v[20:21], v[20:21], v[36:37] op_sel_hi:[1,0]
	v_pk_mul_f32 v[22:23], v[22:23], v[36:37] op_sel_hi:[1,0]
	v_pk_mul_f32 v[24:25], v[24:25], v[36:37] op_sel_hi:[1,0]
	v_cvt_pk_bf16_f32 v18, v18, v19
	v_cvt_pk_bf16_f32 v19, v20, v21
	v_cvt_pk_bf16_f32 v20, v22, v23
	v_cvt_pk_bf16_f32 v21, v24, v25
	s_nop 1
	v_permlane32_swap_b32_e32 v18, v20
	v_permlane32_swap_b32_e32 v19, v21
	global_store_dwordx4 v[34:35], v[18:21], off offset:1024
	v_pk_mul_f32 v[2:3], v[2:3], v[36:37] op_sel_hi:[1,0]
	v_pk_mul_f32 v[4:5], v[4:5], v[36:37] op_sel_hi:[1,0]
	v_pk_mul_f32 v[6:7], v[6:7], v[36:37] op_sel_hi:[1,0]
	v_pk_mul_f32 v[8:9], v[8:9], v[36:37] op_sel_hi:[1,0]
	v_cvt_pk_bf16_f32 v2, v2, v3
	v_cvt_pk_bf16_f32 v3, v4, v5
	v_cvt_pk_bf16_f32 v4, v6, v7
	v_cvt_pk_bf16_f32 v5, v8, v9
	s_nop 1
	v_permlane32_swap_b32_e32 v2, v4
	v_permlane32_swap_b32_e32 v3, v5
	global_store_dwordx4 v[34:35], v[2:5], off offset:1088
	v_pk_mul_f32 v[26:27], v[26:27], v[36:37] op_sel_hi:[1,0]
	v_pk_mul_f32 v[28:29], v[28:29], v[36:37] op_sel_hi:[1,0]
	v_pk_mul_f32 v[30:31], v[30:31], v[36:37] op_sel_hi:[1,0]
	v_pk_mul_f32 v[32:33], v[32:33], v[36:37] op_sel_hi:[1,0]
	v_cvt_pk_bf16_f32 v26, v26, v27
	v_cvt_pk_bf16_f32 v27, v28, v29
	v_cvt_pk_bf16_f32 v28, v30, v31
	v_cvt_pk_bf16_f32 v29, v32, v33
	s_nop 1
	v_permlane32_swap_b32_e32 v26, v28
	v_permlane32_swap_b32_e32 v27, v29
	global_store_dwordx4 v[34:35], v[26:29], off offset:1056
	v_pk_mul_f32 v[10:11], v[10:11], v[36:37] op_sel_hi:[1,0]
	v_pk_mul_f32 v[12:13], v[12:13], v[36:37] op_sel_hi:[1,0]
	v_pk_mul_f32 v[14:15], v[14:15], v[36:37] op_sel_hi:[1,0]
	v_pk_mul_f32 v[16:17], v[16:17], v[36:37] op_sel_hi:[1,0]
	v_cvt_pk_bf16_f32 v10, v10, v11
	v_cvt_pk_bf16_f32 v11, v12, v13
	v_cvt_pk_bf16_f32 v12, v14, v15
	v_cvt_pk_bf16_f32 v13, v16, v17
	s_nop 1
	v_permlane32_swap_b32_e32 v10, v12
	v_permlane32_swap_b32_e32 v11, v13
	global_store_dwordx4 v[34:35], v[10:13], off offset:1120
	s_add_i32 s78, s78, 1
	v_readlane_b32 s74, v246, 3
	v_readlane_b32 s5, v246, 7
	s_nop 3
	s_mul_i32 s4, s78, s74
	s_add_i32 s72, s4, s5
	s_add_i32 s33, s33, s74
	s_cmpk_lt_i32 s72, 0x600
	s_mov_b64 s[94:95], s[10:11]
	v_readlane_b32 s75, v246, 4
	s_cbranch_scc0 .LBB0_469
